# MLA first block: counted lgkmcnt waits per K fragment in the QK MFMA chain instead of one lgkmcnt(0) for all twelve reads
# baseline (speedup 1.0000x reference)
; #define LAS __attribute__((address_space(3)))
; #define MFMA32(a, b, c) __builtin_amdgcn_mfma_f32_32x32x16_bf16((a), (b), (c), 0, 0, 0)
; template <int DQK, int DV, bool CAUSAL, int KT, bool PRIO>
; DI void attn_unit(const bf16_t* Qb, int qpitch, const bf16_t* Kb, int kpitch, const bf16_t* Vtb, int vpitch, bf16_t* Ob, int opitch, int q0, int nt, LAS unsigned char* lds, float kbound, const float* qgain, const int* qpos, float qscale) {
;     ...
;                 if (PRIO) {
;                     constexpr int KSN = DQK / 16, NDB = DV / 32;
;                     f32x16 s0 = negm, s1 = negm;
;                     const LAS unsigned char* kb = lds + buf * KBUF + (64 * hf + r) * KS + h * 16;
;                     const LAS unsigned char* vb = lds + VOFF + buf * VBUF + r * VS + h * 8 + 128 * hf;
;                     bf16x8 kf0[KSN], kf1[KSN], vf[4][NDB];
; #pragma unroll
;                     for (int ks = 0; ks < KSN; ++ks) { kf0[ks] = *(const LAS bf16x8*)(kb + ks * 32); kf1[ks] = *(const LAS bf16x8*)(kb + 32 * KS + ks * 32); }
;                     __builtin_amdgcn_sched_barrier(0); __builtin_amdgcn_s_setprio(1); __builtin_amdgcn_sched_barrier(0);
; #pragma unroll
;                     for (int ks = 0; ks < KSN; ++ks) { s0 = MFMA32(kf0[ks], qf[ks], s0); s1 = MFMA32(kf1[ks], qf[ks], s1); }
;                     __builtin_amdgcn_sched_barrier(0); __builtin_amdgcn_s_setprio(0); __builtin_amdgcn_sched_barrier(0);
; #pragma unroll
;                     for (int q4 = 0; q4 < 4; ++q4)
; #pragma unroll
;                         for (int d = 0; d < NDB; ++d) { const LAS unsigned char* vp = vb + d * 32 * VS + q4 * 32;
;                             const s16x4 lo = *(const LAS s16x4*)vp, hi = *(const LAS s16x4*)(vp + 16); vf[q4][d] = (bf16x8){lo[0], lo[1], lo[2], lo[3], hi[0], hi[1], hi[2], hi[3]}; }
;                     if (CAUSAL && key0 + 63 > qlo) {
; #pragma unroll
;                         for (int i = 0; i < 16; ++i) { const int key = key0 + (i & 3) + 8 * (i >> 2) + 4 * h; if (key > qabs) s0[i] = -1e30f; if (key + 32 > qabs) s1[i] = -1e30f; }
.LBB0_1495:
	ds_read_b128 v[2:5], v194
	ds_read_b128 v[6:9], v194 offset:32
	ds_read_b128 v[10:13], v194 offset:6656
	ds_read_b128 v[140:143], v194 offset:6688
	ds_read_b128 v[144:147], v194 offset:64
	ds_read_b128 v[148:151], v194 offset:96
	ds_read_b128 v[152:155], v194 offset:6720
	ds_read_b128 v[156:159], v194 offset:6752
	ds_read_b128 v[198:201], v194 offset:128
	ds_read_b128 v[202:205], v194 offset:160
	ds_read_b128 v[206:209], v194 offset:6784
	ds_read_b128 v[210:213], v194 offset:6816
	global_load_dwordx4 v[96:99], v[172:173], off
	global_load_dwordx4 v[100:103], v[170:171], off
	global_load_dwordx4 v[104:107], v[168:169], off
	global_load_dwordx4 v[108:111], v[166:167], off
	global_load_dwordx4 v[112:115], v[164:165], off
	v_lshl_add_u64 v[164:165], v[164:165], 0, s[14:15]
	v_lshl_add_u64 v[166:167], v[166:167], 0, s[14:15]
	v_lshl_add_u64 v[168:169], v[168:169], 0, s[16:17]
	v_lshl_add_u64 v[170:171], v[170:171], 0, s[16:17]
	v_lshl_add_u64 v[172:173], v[172:173], 0, s[16:17]
	s_setprio 1
	s_setprio 0
	s_waitcnt lgkmcnt(11)
	v_mfma_f32_32x32x16_bf16 v[80:95], v[2:5], v[116:119], v[48:63]
	s_cmp_le_i32 s71, s69
	s_waitcnt lgkmcnt(9)
	v_mfma_f32_32x32x16_bf16 v[64:79], v[10:13], v[116:119], v[48:63]
	v_mfma_f32_32x32x16_bf16 v[80:95], v[6:9], v[120:123], v[80:95]
	s_waitcnt lgkmcnt(8)
	v_mfma_f32_32x32x16_bf16 v[64:79], v[140:143], v[120:123], v[64:79]
	s_waitcnt lgkmcnt(7)
	v_mfma_f32_32x32x16_bf16 v[80:95], v[144:147], v[124:127], v[80:95]
	s_waitcnt lgkmcnt(5)
	v_mfma_f32_32x32x16_bf16 v[64:79], v[152:155], v[124:127], v[64:79]
	ds_read_b128 v[152:155], v14
	ds_read_b128 v[140:143], v14 offset:32
	v_mfma_f32_32x32x16_bf16 v[80:95], v[148:151], v[128:131], v[80:95]
	s_waitcnt lgkmcnt(6)
	v_mfma_f32_32x32x16_bf16 v[64:79], v[156:159], v[128:131], v[64:79]
	ds_read_b128 v[156:159], v15
	ds_read_b128 v[148:151], v15 offset:32
	ds_read_b128 v[144:147], v14 offset:64
	ds_read_b128 v[10:13], v15 offset:64
	ds_read_b128 v[6:9], v14 offset:96
	ds_read_b128 v[2:5], v15 offset:96
	s_waitcnt lgkmcnt(11)
	v_mfma_f32_32x32x16_bf16 v[80:95], v[198:201], v[132:135], v[80:95]
	s_waitcnt lgkmcnt(9)
	v_mfma_f32_32x32x16_bf16 v[64:79], v[206:209], v[132:135], v[64:79]
	v_mfma_f32_32x32x16_bf16 v[80:95], v[202:205], v[136:139], v[80:95]
	s_waitcnt lgkmcnt(8)
	v_mfma_f32_32x32x16_bf16 v[64:79], v[210:213], v[136:139], v[64:79]
	ds_read_b128 v[214:217], v194 offset:13312
	ds_read_b128 v[218:221], v194 offset:13344
	ds_read_b128 v[222:225], v194 offset:19968
	ds_read_b128 v[226:229], v194 offset:20000
	ds_read_b128 v[230:233], v194 offset:13376
	ds_read_b128 v[234:237], v194 offset:13408
	ds_read_b128 v[238:241], v194 offset:20032
	ds_read_b128 v[242:245], v194 offset:20064
	s_cbranch_scc1 .LBB0_1497
	v_add_u32_e32 v195, s71, v180
	v_subrev_u32_e32 v198, 31, v195
	v_subrev_u32_e32 v197, 63, v195
	v_cmp_le_i32_e32 vcc, v198, v189
	s_nop 6
	v_cndmask_b32_e32 v64, v177, v64, vcc
	v_cmp_lt_i32_e32 vcc, v197, v189
	s_nop 1
	v_cndmask_b32_e32 v81, v177, v81, vcc
	v_cmp_le_i32_e32 vcc, v197, v189
	v_subrev_u32_e32 v197, 30, v195
	s_nop 0
	v_cndmask_b32_e32 v80, v177, v80, vcc
	v_cmp_le_i32_e32 vcc, v197, v189
	v_subrev_u32_e32 v197, 61, v195
	s_nop 0
	v_cndmask_b32_e32 v65, v177, v65, vcc
	v_cmp_le_i32_e32 vcc, v197, v189
	v_subrev_u32_e32 v197, 29, v195
	s_nop 0
	v_cndmask_b32_e32 v82, v177, v82, vcc
	v_cmp_le_i32_e32 vcc, v197, v189
	v_subrev_u32_e32 v197, 60, v195
	s_nop 0
	v_cndmask_b32_e32 v66, v177, v66, vcc
	v_cmp_le_i32_e32 vcc, v197, v189
	v_subrev_u32_e32 v197, 28, v195
	s_nop 0
	v_cndmask_b32_e32 v83, v177, v83, vcc
	v_cmp_le_i32_e32 vcc, v197, v189
	v_subrev_u32_e32 v197, 55, v195
	s_nop 0
	v_cndmask_b32_e32 v67, v177, v67, vcc
	v_cmp_le_i32_e32 vcc, v197, v189
	v_subrev_u32_e32 v197, 23, v195
	s_nop 0
	v_cndmask_b32_e32 v84, v177, v84, vcc
	v_cmp_le_i32_e32 vcc, v197, v189
	v_subrev_u32_e32 v197, 54, v195
	s_nop 0
	v_cndmask_b32_e32 v68, v177, v68, vcc
	v_cmp_le_i32_e32 vcc, v197, v189
	v_subrev_u32_e32 v197, 22, v195
	s_nop 0
	v_cndmask_b32_e32 v85, v177, v85, vcc
	v_cmp_le_i32_e32 vcc, v197, v189
	v_subrev_u32_e32 v197, 53, v195
	s_nop 0
	v_cndmask_b32_e32 v69, v177, v69, vcc
	v_cmp_le_i32_e32 vcc, v197, v189
	v_subrev_u32_e32 v197, 21, v195
	s_nop 0
	v_cndmask_b32_e32 v86, v177, v86, vcc
	v_cmp_le_i32_e32 vcc, v197, v189
	v_subrev_u32_e32 v197, 52, v195
	s_nop 0
	v_cndmask_b32_e32 v70, v177, v70, vcc
	v_cmp_le_i32_e32 vcc, v197, v189
	v_subrev_u32_e32 v197, 20, v195
	s_nop 0
	v_cndmask_b32_e32 v87, v177, v87, vcc
	v_cmp_le_i32_e32 vcc, v197, v189
	v_subrev_u32_e32 v197, 47, v195
	s_nop 0
	v_cndmask_b32_e32 v71, v177, v71, vcc
	v_cmp_le_i32_e32 vcc, v197, v189
	v_add_u32_e32 v197, -15, v195
	s_nop 0
	v_cndmask_b32_e32 v88, v177, v88, vcc
	v_cmp_le_i32_e32 vcc, v197, v189
	v_subrev_u32_e32 v197, 46, v195
	s_nop 0
	v_cndmask_b32_e32 v72, v177, v72, vcc
	v_cmp_le_i32_e32 vcc, v197, v189
	v_add_u32_e32 v197, -14, v195
	s_nop 0
	v_cndmask_b32_e32 v89, v177, v89, vcc
	v_cmp_le_i32_e32 vcc, v197, v189
	v_subrev_u32_e32 v197, 45, v195
	s_nop 0
	v_cndmask_b32_e32 v73, v177, v73, vcc
	v_cmp_le_i32_e32 vcc, v197, v189
	v_add_u32_e32 v197, -13, v195
	s_nop 0
	v_cndmask_b32_e32 v90, v177, v90, vcc
	v_cmp_le_i32_e32 vcc, v197, v189
	v_subrev_u32_e32 v197, 44, v195
	s_nop 0
	v_cndmask_b32_e32 v74, v177, v74, vcc
	v_cmp_le_i32_e32 vcc, v197, v189
	v_add_u32_e32 v197, -12, v195
	s_nop 0
	v_cndmask_b32_e32 v91, v177, v91, vcc
	v_cmp_le_i32_e32 vcc, v197, v189
	v_subrev_u32_e32 v197, 39, v195
	s_nop 0
	v_cndmask_b32_e32 v75, v177, v75, vcc
	v_cmp_le_i32_e32 vcc, v197, v189
	v_add_u32_e32 v197, -7, v195
	s_nop 0
	v_cndmask_b32_e32 v92, v177, v92, vcc
	v_cmp_le_i32_e32 vcc, v197, v189
	v_subrev_u32_e32 v197, 38, v195
	s_nop 0
	v_cndmask_b32_e32 v76, v177, v76, vcc
	v_cmp_le_i32_e32 vcc, v197, v189
	v_add_u32_e32 v197, -6, v195
	s_nop 0
	v_cndmask_b32_e32 v93, v177, v93, vcc
	v_cmp_le_i32_e32 vcc, v197, v189
	v_subrev_u32_e32 v197, 37, v195
	s_nop 0
	v_cndmask_b32_e32 v77, v177, v77, vcc
	v_cmp_le_i32_e32 vcc, v197, v189
	v_add_u32_e32 v197, -5, v195
	s_nop 0
	v_cndmask_b32_e32 v94, v177, v94, vcc
	v_cmp_le_i32_e32 vcc, v197, v189
	v_subrev_u32_e32 v197, 36, v195
	v_add_u32_e32 v195, -4, v195
	v_cndmask_b32_e32 v78, v177, v78, vcc
	v_cmp_le_i32_e32 vcc, v197, v189
	s_nop 1
	v_cndmask_b32_e32 v95, v177, v95, vcc
	v_cmp_le_i32_e32 vcc, v195, v189
	s_nop 1
	v_cndmask_b32_e32 v79, v177, v79, vcc
